# gather head loop: per-half scalars (a[m], next expert ids) broadcast by ds_bpermute instead of readlane+mov+cndmask; row addresses by 24-bit mad + SGPR-base loads instead of 64-bit mad/add
# baseline (speedup 1.0000x reference)
.LBB0_324:
	s_nop 0
	v_readlane_b32 s0, v249, 46
	v_readlane_b32 s1, v249, 47
	s_and_b64 vcc, exec, s[0:1]
	s_cbranch_vccz .LBB0_345
	v_mov_b32_e32 v1, v220
	v_readlane_b32 s0, v249, 0
	s_nop 0
	v_ashrrev_i32_e32 v0, 6, v1
	v_lshl_add_u32 v116, s0, 2, v0
	s_movk_i32 s0, 0x4200
	v_cmp_gt_i32_e32 vcc, s0, v116
	s_and_saveexec_b64 s[0:1], vcc
	s_cbranch_execz .LBB0_344
	v_readlane_b32 s2, v249, 37
	v_readlane_b32 s26, v249, 30
	v_readlane_b32 s3, v249, 38
	v_readlane_b32 s27, v249, 31
	s_mul_hi_i32 s4, s2, 0x1400000
	s_mul_i32 s5, s2, 0x1400000
	s_load_dwordx2 s[2:3], s[26:27], 0x160
	v_and_b32_e32 v6, 31, v1
	v_mul_u32_u24_e32 v2, 24, v6
	v_mov_b32_e32 v3, v80
	v_and_b32_e32 v81, 63, v1
	v_and_b32_e32 v255, 32, v81
	v_lshlrev_b32_e32 v255, 2, v255
	s_waitcnt lgkmcnt(0)
	s_add_u32 s2, s2, s5
	s_addc_u32 s3, s3, s4
	v_lshl_add_u64 v[118:119], s[2:3], 0, v[2:3]
	v_mov_b32_e32 v254, v2
	s_mov_b64 s[52:53], s[2:3]
	v_lshlrev_b32_e32 v2, 4, v6
	s_getpc_b64 s[4:5]
	s_add_u32 s4, s4, c_cand@rel32@lo+4
	s_addc_u32 s5, s5, c_cand@rel32@hi+12
	v_lshl_add_u64 v[120:121], s[2:3], 0, v[2:3]
	v_mov_b32_e32 v253, v2
	s_load_dwordx4 s[12:15], s[26:27], 0x90
	s_load_dwordx2 s[2:3], s[26:27], 0xc8
	global_load_ubyte v2, v81, s[4:5]
	v_readlane_b32 s16, v249, 13
	s_sub_i32 s10, s16, 19
	s_cmp_lt_u32 s10, 6
	s_cselect_b64 s[4:5], -1, 0
	s_cmp_gt_u32 s10, 5
	v_readlane_b32 s10, v249, 39
	v_readlane_b32 s11, v249, 40
	s_cselect_b64 s[20:21], -1, 0
	s_lshl_b64 s[10:11], s[10:11], 2
	s_waitcnt lgkmcnt(0)
	s_add_u32 s22, s14, s10
	s_addc_u32 s23, s15, s11
	s_add_u32 s24, s12, s10
	s_addc_u32 s25, s13, s11
	s_load_dwordx2 s[10:11], s[26:27], 0x140
	v_lshlrev_b32_e32 v3, 3, v81
	v_lshlrev_b32_e32 v4, 6, v6
	v_mov_b32_e32 v5, v80
	v_lshl_or_b32 v239, v0, 12, v3
	s_waitcnt lgkmcnt(0)
	v_lshl_add_u64 v[122:123], s[10:11], 0, v[4:5]
	v_and_b32_e32 v3, 3, v1
	v_and_b32_e32 v4, 64, v229
	v_cmp_eq_u32_e64 s[12:13], 0, v3
	v_xor_b32_e32 v3, 4, v229
	v_add_u32_e32 v4, 64, v4
	v_cmp_lt_i32_e32 vcc, v3, v4
	v_readlane_b32 s18, v249, 15
	v_readlane_b32 s19, v249, 16
	v_cndmask_b32_e32 v3, v229, v3, vcc
	v_lshlrev_b32_e32 v240, 2, v3
	v_xor_b32_e32 v3, 8, v229
	v_cmp_lt_i32_e32 vcc, v3, v4
	v_readlane_b32 s17, v249, 14
	v_cmp_lt_u32_e64 s[6:7], 31, v81
	v_cndmask_b32_e32 v3, v229, v3, vcc
	v_lshlrev_b32_e32 v241, 2, v3
	v_xor_b32_e32 v3, 16, v229
	v_cmp_lt_i32_e32 vcc, v3, v4
	v_cmp_gt_u32_e64 s[8:9], 32, v81
	v_cmp_gt_u32_e64 s[10:11], 50, v81
	v_cndmask_b32_e32 v3, v229, v3, vcc
	v_lshlrev_b32_e32 v242, 2, v3
	v_xor_b32_e32 v3, 32, v229
	v_cmp_lt_i32_e32 vcc, v3, v4
	s_waitcnt vmcnt(0)
	v_and_b32_e32 v0, 15, v2
	v_cndmask_b32_e32 v3, v229, v3, vcc
	v_lshlrev_b32_e32 v243, 2, v3
	v_and_b32_e32 v3, 16, v1
	v_cmp_eq_u32_e64 s[14:15], 0, v3
	v_and_b32_e32 v3, 8, v1
	v_and_b32_e32 v1, 4, v1
	v_cmp_eq_u32_e64 s[18:19], 0, v1
	v_xor_b32_e32 v1, 2, v229
	v_cmp_lt_i32_e32 vcc, v1, v4
	v_lshrrev_b32_e32 v2, 4, v2
	v_cmp_eq_u32_e64 s[16:17], 0, v3
	v_cndmask_b32_e32 v1, v229, v1, vcc
	v_lshlrev_b32_e32 v244, 2, v1
	v_xor_b32_e32 v1, 1, v229
	v_cmp_lt_i32_e32 vcc, v1, v4
	v_lshlrev_b32_e32 v4, 7, v6
	v_lshl_add_u64 v[124:125], s[24:25], 0, v[4:5]
	v_cndmask_b32_e32 v1, v229, v1, vcc
	v_lshlrev_b32_e32 v245, 2, v1
	v_lshl_add_u64 v[126:127], s[22:23], 0, v[4:5]
	v_lshl_add_u64 v[128:129], s[2:3], 0, v[4:5]
	s_mov_b64 s[22:23], 0
	v_lshlrev_b32_e32 v130, 2, v2
	v_lshlrev_b32_e32 v132, 2, v0
	s_branch .LBB0_328

.LBB0_329:
	s_or_b64 exec, exec, s[2:3]
	v_mad_u32_u24 v0, v0, s28, v253
	v_mad_u32_u24 v4, v2, s28, v253
	v_mad_u32_u24 v2, v3, s28, v253
	v_mad_u32_u24 v8, v6, s28, v253
	v_mad_u32_u24 v6, v7, s28, v253
	v_mad_u32_u24 v12, v10, s28, v253
	v_mad_u32_u24 v10, v11, s28, v253
	v_mad_u32_u24 v14, v14, s28, v253
	s_brev_b32 s2, -2
	s_nop 0
	v_bfi_b32 v16, s2, v19, v16
	v_mul_f32_e32 v18, 0.5, v18
	v_add_f32_e32 v16, 1.0, v16
	v_mul_f32_e32 v16, v18, v16
	v_mul_f32_e32 v16, v17, v16
	v_mul_f32_e32 v117, 0x3daaaaab, v16
	s_nop 0
	s_waitcnt vmcnt(23)
	v_cvt_scalef32_pk_f32_fp4 v[18:19], v110, 1.0
	v_add_u32_e32 v17, 0, v255
	ds_bpermute_b32 v16, v17, v117
	s_waitcnt lgkmcnt(0)
	v_cvt_scalef32_pk_f32_fp4 v[20:21], v110, 1.0 op_sel:[1,0,0]
	v_cvt_scalef32_pk_f32_fp4 v[22:23], v110, 1.0 op_sel:[0,1,0]
	v_cvt_scalef32_pk_f32_fp4 v[24:25], v110, 1.0 op_sel:[1,1,0]
	v_cvt_scalef32_pk_f32_fp4 v[26:27], v111, 1.0
	v_cvt_scalef32_pk_f32_fp4 v[28:29], v111, 1.0 op_sel:[1,0,0]
	v_cvt_scalef32_pk_f32_fp4 v[30:31], v111, 1.0 op_sel:[0,1,0]
	v_cvt_scalef32_pk_f32_fp4 v[110:111], v111, 1.0 op_sel:[1,1,0]
	v_pk_fma_f32 v[110:111], v[16:17], v[110:111], v[202:203] op_sel_hi:[0,1,1]
	v_cvt_scalef32_pk_f32_fp4 v[202:203], v112, 1.0
	v_pk_fma_f32 v[200:201], v[16:17], v[202:203], v[200:201] op_sel_hi:[0,1,1]
	v_cvt_scalef32_pk_f32_fp4 v[202:203], v112, 1.0 op_sel:[1,0,0]
	v_pk_fma_f32 v[198:199], v[16:17], v[202:203], v[198:199] op_sel_hi:[0,1,1]
	v_cvt_scalef32_pk_f32_fp4 v[202:203], v112, 1.0 op_sel:[0,1,0]
	v_pk_fma_f32 v[196:197], v[16:17], v[202:203], v[196:197] op_sel_hi:[0,1,1]
	v_cvt_scalef32_pk_f32_fp4 v[202:203], v112, 1.0 op_sel:[1,1,0]
	v_pk_fma_f32 v[194:195], v[16:17], v[202:203], v[194:195] op_sel_hi:[0,1,1]
	v_cvt_scalef32_pk_f32_fp4 v[202:203], v113, 1.0
	v_pk_fma_f32 v[192:193], v[16:17], v[202:203], v[192:193] op_sel_hi:[0,1,1]
	v_cvt_scalef32_pk_f32_fp4 v[202:203], v113, 1.0 op_sel:[1,0,0]
	v_pk_fma_f32 v[190:191], v[16:17], v[202:203], v[190:191] op_sel_hi:[0,1,1]
	v_cvt_scalef32_pk_f32_fp4 v[202:203], v113, 1.0 op_sel:[0,1,0]
	v_pk_fma_f32 v[188:189], v[16:17], v[202:203], v[188:189] op_sel_hi:[0,1,1]
	v_cvt_scalef32_pk_f32_fp4 v[112:113], v113, 1.0 op_sel:[1,1,0]
	v_pk_fma_f32 v[18:19], v[18:19], v[16:17], v[216:217] op_sel_hi:[1,0,1]
	v_pk_fma_f32 v[20:21], v[20:21], v[16:17], v[214:215] op_sel_hi:[1,0,1]
	v_pk_fma_f32 v[22:23], v[22:23], v[16:17], v[212:213] op_sel_hi:[1,0,1]
	v_pk_fma_f32 v[24:25], v[16:17], v[24:25], v[210:211] op_sel_hi:[0,1,1]
	v_pk_fma_f32 v[26:27], v[16:17], v[26:27], v[208:209] op_sel_hi:[0,1,1]
	v_pk_fma_f32 v[28:29], v[16:17], v[28:29], v[206:207] op_sel_hi:[0,1,1]
	v_pk_fma_f32 v[30:31], v[16:17], v[30:31], v[204:205] op_sel_hi:[0,1,1]
	v_pk_fma_f32 v[16:17], v[16:17], v[112:113], v[176:177] op_sel_hi:[0,1,1]
	s_waitcnt vmcnt(22)
	v_cvt_scalef32_pk_f32_fp4 v[176:177], v106, 1.0
	v_add_u32_e32 v113, 16, v255
	ds_bpermute_b32 v112, v113, v117
	s_waitcnt lgkmcnt(0)
	v_pk_fma_f32 v[18:19], v[176:177], v[112:113], v[18:19] op_sel_hi:[1,0,1]
	v_cvt_scalef32_pk_f32_fp4 v[176:177], v106, 1.0 op_sel:[1,0,0]
	v_pk_fma_f32 v[20:21], v[176:177], v[112:113], v[20:21] op_sel_hi:[1,0,1]
	v_cvt_scalef32_pk_f32_fp4 v[176:177], v106, 1.0 op_sel:[0,1,0]
	v_pk_fma_f32 v[22:23], v[176:177], v[112:113], v[22:23] op_sel_hi:[1,0,1]
	v_cvt_scalef32_pk_f32_fp4 v[176:177], v106, 1.0 op_sel:[1,1,0]
	v_pk_fma_f32 v[24:25], v[112:113], v[176:177], v[24:25] op_sel_hi:[0,1,1]
	v_cvt_scalef32_pk_f32_fp4 v[176:177], v107, 1.0
	v_pk_fma_f32 v[26:27], v[112:113], v[176:177], v[26:27] op_sel_hi:[0,1,1]
	v_cvt_scalef32_pk_f32_fp4 v[176:177], v107, 1.0 op_sel:[1,0,0]
	v_pk_fma_f32 v[28:29], v[112:113], v[176:177], v[28:29] op_sel_hi:[0,1,1]
	v_cvt_scalef32_pk_f32_fp4 v[176:177], v107, 1.0 op_sel:[0,1,0]
	v_pk_fma_f32 v[30:31], v[112:113], v[176:177], v[30:31] op_sel_hi:[0,1,1]
	v_cvt_scalef32_pk_f32_fp4 v[176:177], v108, 1.0 op_sel:[1,0,0]
	v_pk_fma_f32 v[176:177], v[112:113], v[176:177], v[198:199] op_sel_hi:[0,1,1]
	v_cvt_scalef32_pk_f32_fp4 v[198:199], v108, 1.0 op_sel:[0,1,0]
	v_pk_fma_f32 v[196:197], v[112:113], v[198:199], v[196:197] op_sel_hi:[0,1,1]
	v_cvt_scalef32_pk_f32_fp4 v[198:199], v108, 1.0 op_sel:[1,1,0]
	v_pk_fma_f32 v[194:195], v[112:113], v[198:199], v[194:195] op_sel_hi:[0,1,1]
	v_cvt_scalef32_pk_f32_fp4 v[198:199], v109, 1.0
	v_cvt_scalef32_pk_f32_fp4 v[106:107], v107, 1.0 op_sel:[1,1,0]
	v_pk_fma_f32 v[192:193], v[112:113], v[198:199], v[192:193] op_sel_hi:[0,1,1]
	v_cvt_scalef32_pk_f32_fp4 v[198:199], v109, 1.0 op_sel:[1,0,0]
	v_pk_fma_f32 v[106:107], v[112:113], v[106:107], v[110:111] op_sel_hi:[0,1,1]
	v_cvt_scalef32_pk_f32_fp4 v[110:111], v108, 1.0
	v_pk_fma_f32 v[190:191], v[112:113], v[198:199], v[190:191] op_sel_hi:[0,1,1]
	v_cvt_scalef32_pk_f32_fp4 v[198:199], v109, 1.0 op_sel:[0,1,0]
	v_pk_fma_f32 v[110:111], v[112:113], v[110:111], v[200:201] op_sel_hi:[0,1,1]
	v_pk_fma_f32 v[188:189], v[112:113], v[198:199], v[188:189] op_sel_hi:[0,1,1]
	v_cvt_scalef32_pk_f32_fp4 v[108:109], v109, 1.0 op_sel:[1,1,0]
	v_pk_fma_f32 v[16:17], v[112:113], v[108:109], v[16:17] op_sel_hi:[0,1,1]
	s_waitcnt vmcnt(21)
	v_cvt_scalef32_pk_f32_fp4 v[112:113], v102, 1.0
	v_add_u32_e32 v109, 32, v255
	ds_bpermute_b32 v108, v109, v117
	s_waitcnt lgkmcnt(0)
	v_pk_fma_f32 v[18:19], v[112:113], v[108:109], v[18:19] op_sel_hi:[1,0,1]
	v_cvt_scalef32_pk_f32_fp4 v[112:113], v102, 1.0 op_sel:[1,0,0]
	v_pk_fma_f32 v[20:21], v[112:113], v[108:109], v[20:21] op_sel_hi:[1,0,1]
	v_cvt_scalef32_pk_f32_fp4 v[112:113], v102, 1.0 op_sel:[0,1,0]
	v_pk_fma_f32 v[22:23], v[112:113], v[108:109], v[22:23] op_sel_hi:[1,0,1]
	v_cvt_scalef32_pk_f32_fp4 v[112:113], v102, 1.0 op_sel:[1,1,0]
	v_pk_fma_f32 v[24:25], v[108:109], v[112:113], v[24:25] op_sel_hi:[0,1,1]
	v_cvt_scalef32_pk_f32_fp4 v[112:113], v103, 1.0
	v_pk_fma_f32 v[26:27], v[108:109], v[112:113], v[26:27] op_sel_hi:[0,1,1]
	v_cvt_scalef32_pk_f32_fp4 v[112:113], v103, 1.0 op_sel:[1,0,0]
	v_pk_fma_f32 v[28:29], v[108:109], v[112:113], v[28:29] op_sel_hi:[0,1,1]
	v_cvt_scalef32_pk_f32_fp4 v[112:113], v103, 1.0 op_sel:[0,1,0]
	v_cvt_scalef32_pk_f32_fp4 v[102:103], v103, 1.0 op_sel:[1,1,0]
	v_pk_fma_f32 v[102:103], v[108:109], v[102:103], v[106:107] op_sel_hi:[0,1,1]
	v_cvt_scalef32_pk_f32_fp4 v[106:107], v104, 1.0
	v_pk_fma_f32 v[106:107], v[108:109], v[106:107], v[110:111] op_sel_hi:[0,1,1]
	v_cvt_scalef32_pk_f32_fp4 v[110:111], v104, 1.0 op_sel:[1,0,0]
	v_pk_fma_f32 v[110:111], v[108:109], v[110:111], v[176:177] op_sel_hi:[0,1,1]
	v_cvt_scalef32_pk_f32_fp4 v[176:177], v104, 1.0 op_sel:[1,1,0]
	v_pk_fma_f32 v[176:177], v[108:109], v[176:177], v[194:195] op_sel_hi:[0,1,1]
	v_cvt_scalef32_pk_f32_fp4 v[194:195], v105, 1.0
	v_pk_fma_f32 v[192:193], v[108:109], v[194:195], v[192:193] op_sel_hi:[0,1,1]
	v_cvt_scalef32_pk_f32_fp4 v[194:195], v105, 1.0 op_sel:[1,0,0]
	v_pk_fma_f32 v[30:31], v[108:109], v[112:113], v[30:31] op_sel_hi:[0,1,1]
	v_cvt_scalef32_pk_f32_fp4 v[112:113], v104, 1.0 op_sel:[0,1,0]
	v_pk_fma_f32 v[190:191], v[108:109], v[194:195], v[190:191] op_sel_hi:[0,1,1]
	v_cvt_scalef32_pk_f32_fp4 v[194:195], v105, 1.0 op_sel:[0,1,0]
	v_pk_fma_f32 v[112:113], v[108:109], v[112:113], v[196:197] op_sel_hi:[0,1,1]
	v_pk_fma_f32 v[188:189], v[108:109], v[194:195], v[188:189] op_sel_hi:[0,1,1]
	v_cvt_scalef32_pk_f32_fp4 v[104:105], v105, 1.0 op_sel:[1,1,0]
	v_pk_fma_f32 v[16:17], v[108:109], v[104:105], v[16:17] op_sel_hi:[0,1,1]
	s_waitcnt vmcnt(20)
	v_cvt_scalef32_pk_f32_fp4 v[108:109], v98, 1.0
	v_add_u32_e32 v105, 48, v255
	ds_bpermute_b32 v104, v105, v117
	s_waitcnt lgkmcnt(0)
	v_pk_fma_f32 v[18:19], v[108:109], v[104:105], v[18:19] op_sel_hi:[1,0,1]
	v_cvt_scalef32_pk_f32_fp4 v[108:109], v98, 1.0 op_sel:[1,0,0]
	v_pk_fma_f32 v[20:21], v[108:109], v[104:105], v[20:21] op_sel_hi:[1,0,1]
	v_cvt_scalef32_pk_f32_fp4 v[108:109], v98, 1.0 op_sel:[0,1,0]
	v_pk_fma_f32 v[22:23], v[108:109], v[104:105], v[22:23] op_sel_hi:[1,0,1]
	v_cvt_scalef32_pk_f32_fp4 v[108:109], v98, 1.0 op_sel:[1,1,0]
	v_pk_fma_f32 v[24:25], v[104:105], v[108:109], v[24:25] op_sel_hi:[0,1,1]
	v_cvt_scalef32_pk_f32_fp4 v[108:109], v99, 1.0
	v_pk_fma_f32 v[26:27], v[104:105], v[108:109], v[26:27] op_sel_hi:[0,1,1]
	v_cvt_scalef32_pk_f32_fp4 v[108:109], v99, 1.0 op_sel:[1,0,0]
	v_pk_fma_f32 v[28:29], v[104:105], v[108:109], v[28:29] op_sel_hi:[0,1,1]
	v_cvt_scalef32_pk_f32_fp4 v[108:109], v99, 1.0 op_sel:[0,1,0]
	v_cvt_scalef32_pk_f32_fp4 v[98:99], v99, 1.0 op_sel:[1,1,0]
	v_pk_fma_f32 v[98:99], v[104:105], v[98:99], v[102:103] op_sel_hi:[0,1,1]
	v_cvt_scalef32_pk_f32_fp4 v[102:103], v100, 1.0
	v_pk_fma_f32 v[102:103], v[104:105], v[102:103], v[106:107] op_sel_hi:[0,1,1]
	v_cvt_scalef32_pk_f32_fp4 v[106:107], v100, 1.0 op_sel:[1,0,0]
	v_pk_fma_f32 v[106:107], v[104:105], v[106:107], v[110:111] op_sel_hi:[0,1,1]
	v_cvt_scalef32_pk_f32_fp4 v[110:111], v100, 1.0 op_sel:[1,1,0]
	v_pk_fma_f32 v[30:31], v[104:105], v[108:109], v[30:31] op_sel_hi:[0,1,1]
	v_cvt_scalef32_pk_f32_fp4 v[108:109], v100, 1.0 op_sel:[0,1,0]
	v_pk_fma_f32 v[110:111], v[104:105], v[110:111], v[176:177] op_sel_hi:[0,1,1]
	v_cvt_scalef32_pk_f32_fp4 v[176:177], v101, 1.0 op_sel:[1,0,0]
	v_pk_fma_f32 v[108:109], v[104:105], v[108:109], v[112:113] op_sel_hi:[0,1,1]
	v_cvt_scalef32_pk_f32_fp4 v[112:113], v101, 1.0
	v_pk_fma_f32 v[176:177], v[104:105], v[176:177], v[190:191] op_sel_hi:[0,1,1]
	v_cvt_scalef32_pk_f32_fp4 v[190:191], v101, 1.0 op_sel:[0,1,0]
	v_pk_fma_f32 v[112:113], v[104:105], v[112:113], v[192:193] op_sel_hi:[0,1,1]
	v_pk_fma_f32 v[188:189], v[104:105], v[190:191], v[188:189] op_sel_hi:[0,1,1]
	v_cvt_scalef32_pk_f32_fp4 v[100:101], v101, 1.0 op_sel:[1,1,0]
	v_pk_fma_f32 v[16:17], v[104:105], v[100:101], v[16:17] op_sel_hi:[0,1,1]
	s_waitcnt vmcnt(19)
	v_cvt_scalef32_pk_f32_fp4 v[104:105], v94, 1.0
	v_add_u32_e32 v101, 64, v255
	ds_bpermute_b32 v100, v101, v117
	s_waitcnt lgkmcnt(0)
	v_pk_fma_f32 v[18:19], v[104:105], v[100:101], v[18:19] op_sel_hi:[1,0,1]
	v_cvt_scalef32_pk_f32_fp4 v[104:105], v94, 1.0 op_sel:[1,0,0]
	v_pk_fma_f32 v[20:21], v[104:105], v[100:101], v[20:21] op_sel_hi:[1,0,1]
	v_cvt_scalef32_pk_f32_fp4 v[104:105], v94, 1.0 op_sel:[0,1,0]
	v_pk_fma_f32 v[22:23], v[104:105], v[100:101], v[22:23] op_sel_hi:[1,0,1]
	v_cvt_scalef32_pk_f32_fp4 v[104:105], v94, 1.0 op_sel:[1,1,0]
	v_pk_fma_f32 v[24:25], v[100:101], v[104:105], v[24:25] op_sel_hi:[0,1,1]
	v_cvt_scalef32_pk_f32_fp4 v[104:105], v95, 1.0
	v_pk_fma_f32 v[26:27], v[100:101], v[104:105], v[26:27] op_sel_hi:[0,1,1]
	v_cvt_scalef32_pk_f32_fp4 v[104:105], v95, 1.0 op_sel:[1,0,0]
	v_pk_fma_f32 v[28:29], v[100:101], v[104:105], v[28:29] op_sel_hi:[0,1,1]
	v_cvt_scalef32_pk_f32_fp4 v[104:105], v95, 1.0 op_sel:[0,1,0]
	v_cvt_scalef32_pk_f32_fp4 v[94:95], v95, 1.0 op_sel:[1,1,0]
	v_pk_fma_f32 v[94:95], v[100:101], v[94:95], v[98:99] op_sel_hi:[0,1,1]
	v_cvt_scalef32_pk_f32_fp4 v[98:99], v96, 1.0
	v_pk_fma_f32 v[30:31], v[100:101], v[104:105], v[30:31] op_sel_hi:[0,1,1]
	v_pk_fma_f32 v[98:99], v[100:101], v[98:99], v[102:103] op_sel_hi:[0,1,1]
	v_cvt_scalef32_pk_f32_fp4 v[102:103], v96, 1.0 op_sel:[1,0,0]
	v_cvt_scalef32_pk_f32_fp4 v[104:105], v96, 1.0 op_sel:[0,1,0]
	v_pk_fma_f32 v[102:103], v[100:101], v[102:103], v[106:107] op_sel_hi:[0,1,1]
	v_pk_fma_f32 v[104:105], v[100:101], v[104:105], v[108:109] op_sel_hi:[0,1,1]
	v_cvt_scalef32_pk_f32_fp4 v[106:107], v96, 1.0 op_sel:[1,1,0]
	v_cvt_scalef32_pk_f32_fp4 v[108:109], v97, 1.0
	v_pk_fma_f32 v[106:107], v[100:101], v[106:107], v[110:111] op_sel_hi:[0,1,1]
	v_pk_fma_f32 v[108:109], v[100:101], v[108:109], v[112:113] op_sel_hi:[0,1,1]
	v_cvt_scalef32_pk_f32_fp4 v[110:111], v97, 1.0 op_sel:[1,0,0]
	v_cvt_scalef32_pk_f32_fp4 v[112:113], v97, 1.0 op_sel:[0,1,0]
	v_pk_fma_f32 v[110:111], v[100:101], v[110:111], v[176:177] op_sel_hi:[0,1,1]
	v_pk_fma_f32 v[112:113], v[100:101], v[112:113], v[188:189] op_sel_hi:[0,1,1]
	v_cvt_scalef32_pk_f32_fp4 v[96:97], v97, 1.0 op_sel:[1,1,0]
	v_pk_fma_f32 v[16:17], v[100:101], v[96:97], v[16:17] op_sel_hi:[0,1,1]
	s_waitcnt vmcnt(18)
	v_cvt_scalef32_pk_f32_fp4 v[100:101], v90, 1.0
	v_add_u32_e32 v97, 80, v255
	ds_bpermute_b32 v96, v97, v117
	s_waitcnt lgkmcnt(0)
	v_pk_fma_f32 v[18:19], v[100:101], v[96:97], v[18:19] op_sel_hi:[1,0,1]
	v_cvt_scalef32_pk_f32_fp4 v[100:101], v90, 1.0 op_sel:[1,0,0]
	v_pk_fma_f32 v[20:21], v[100:101], v[96:97], v[20:21] op_sel_hi:[1,0,1]
	v_cvt_scalef32_pk_f32_fp4 v[100:101], v90, 1.0 op_sel:[0,1,0]
	v_pk_fma_f32 v[22:23], v[100:101], v[96:97], v[22:23] op_sel_hi:[1,0,1]
	v_cvt_scalef32_pk_f32_fp4 v[100:101], v90, 1.0 op_sel:[1,1,0]
	v_pk_fma_f32 v[24:25], v[96:97], v[100:101], v[24:25] op_sel_hi:[0,1,1]
	v_cvt_scalef32_pk_f32_fp4 v[100:101], v91, 1.0
	v_pk_fma_f32 v[26:27], v[96:97], v[100:101], v[26:27] op_sel_hi:[0,1,1]
	v_cvt_scalef32_pk_f32_fp4 v[100:101], v91, 1.0 op_sel:[1,0,0]
	v_pk_fma_f32 v[28:29], v[96:97], v[100:101], v[28:29] op_sel_hi:[0,1,1]
	v_cvt_scalef32_pk_f32_fp4 v[100:101], v91, 1.0 op_sel:[0,1,0]
	v_cvt_scalef32_pk_f32_fp4 v[90:91], v91, 1.0 op_sel:[1,1,0]
	v_pk_fma_f32 v[90:91], v[96:97], v[90:91], v[94:95] op_sel_hi:[0,1,1]
	v_cvt_scalef32_pk_f32_fp4 v[94:95], v92, 1.0
	v_pk_fma_f32 v[30:31], v[96:97], v[100:101], v[30:31] op_sel_hi:[0,1,1]
	v_pk_fma_f32 v[94:95], v[96:97], v[94:95], v[98:99] op_sel_hi:[0,1,1]
	v_cvt_scalef32_pk_f32_fp4 v[98:99], v92, 1.0 op_sel:[1,0,0]
	v_cvt_scalef32_pk_f32_fp4 v[100:101], v92, 1.0 op_sel:[0,1,0]
	v_pk_fma_f32 v[98:99], v[96:97], v[98:99], v[102:103] op_sel_hi:[0,1,1]
	v_pk_fma_f32 v[100:101], v[96:97], v[100:101], v[104:105] op_sel_hi:[0,1,1]
	v_cvt_scalef32_pk_f32_fp4 v[102:103], v92, 1.0 op_sel:[1,1,0]
	v_cvt_scalef32_pk_f32_fp4 v[104:105], v93, 1.0
	v_pk_fma_f32 v[102:103], v[96:97], v[102:103], v[106:107] op_sel_hi:[0,1,1]
	v_pk_fma_f32 v[104:105], v[96:97], v[104:105], v[108:109] op_sel_hi:[0,1,1]
	v_cvt_scalef32_pk_f32_fp4 v[106:107], v93, 1.0 op_sel:[1,0,0]
	v_cvt_scalef32_pk_f32_fp4 v[108:109], v93, 1.0 op_sel:[0,1,0]
	v_pk_fma_f32 v[106:107], v[96:97], v[106:107], v[110:111] op_sel_hi:[0,1,1]
	v_pk_fma_f32 v[108:109], v[96:97], v[108:109], v[112:113] op_sel_hi:[0,1,1]
	v_cvt_scalef32_pk_f32_fp4 v[92:93], v93, 1.0 op_sel:[1,1,0]
	v_pk_fma_f32 v[16:17], v[96:97], v[92:93], v[16:17] op_sel_hi:[0,1,1]
	s_waitcnt vmcnt(17)
	v_cvt_scalef32_pk_f32_fp4 v[96:97], v86, 1.0
	v_add_u32_e32 v93, 96, v255
	ds_bpermute_b32 v92, v93, v117
	s_waitcnt lgkmcnt(0)
	v_pk_fma_f32 v[18:19], v[96:97], v[92:93], v[18:19] op_sel_hi:[1,0,1]
	v_cvt_scalef32_pk_f32_fp4 v[96:97], v86, 1.0 op_sel:[1,0,0]
	v_pk_fma_f32 v[20:21], v[96:97], v[92:93], v[20:21] op_sel_hi:[1,0,1]
	v_cvt_scalef32_pk_f32_fp4 v[96:97], v86, 1.0 op_sel:[0,1,0]
	v_pk_fma_f32 v[22:23], v[96:97], v[92:93], v[22:23] op_sel_hi:[1,0,1]
	v_cvt_scalef32_pk_f32_fp4 v[96:97], v86, 1.0 op_sel:[1,1,0]
	v_pk_fma_f32 v[24:25], v[92:93], v[96:97], v[24:25] op_sel_hi:[0,1,1]
	v_cvt_scalef32_pk_f32_fp4 v[96:97], v87, 1.0
	v_pk_fma_f32 v[26:27], v[92:93], v[96:97], v[26:27] op_sel_hi:[0,1,1]
	v_cvt_scalef32_pk_f32_fp4 v[96:97], v87, 1.0 op_sel:[1,0,0]
	v_pk_fma_f32 v[28:29], v[92:93], v[96:97], v[28:29] op_sel_hi:[0,1,1]
	v_cvt_scalef32_pk_f32_fp4 v[96:97], v87, 1.0 op_sel:[0,1,0]
	v_cvt_scalef32_pk_f32_fp4 v[86:87], v87, 1.0 op_sel:[1,1,0]
	v_pk_fma_f32 v[86:87], v[92:93], v[86:87], v[90:91] op_sel_hi:[0,1,1]
	v_cvt_scalef32_pk_f32_fp4 v[90:91], v88, 1.0
	v_pk_fma_f32 v[30:31], v[92:93], v[96:97], v[30:31] op_sel_hi:[0,1,1]
	v_pk_fma_f32 v[90:91], v[92:93], v[90:91], v[94:95] op_sel_hi:[0,1,1]
	v_cvt_scalef32_pk_f32_fp4 v[94:95], v88, 1.0 op_sel:[1,0,0]
	v_cvt_scalef32_pk_f32_fp4 v[96:97], v88, 1.0 op_sel:[0,1,0]
	v_pk_fma_f32 v[94:95], v[92:93], v[94:95], v[98:99] op_sel_hi:[0,1,1]
	v_pk_fma_f32 v[96:97], v[92:93], v[96:97], v[100:101] op_sel_hi:[0,1,1]
	v_cvt_scalef32_pk_f32_fp4 v[98:99], v88, 1.0 op_sel:[1,1,0]
	v_cvt_scalef32_pk_f32_fp4 v[100:101], v89, 1.0
	v_pk_fma_f32 v[98:99], v[92:93], v[98:99], v[102:103] op_sel_hi:[0,1,1]
	v_pk_fma_f32 v[100:101], v[92:93], v[100:101], v[104:105] op_sel_hi:[0,1,1]
	v_cvt_scalef32_pk_f32_fp4 v[102:103], v89, 1.0 op_sel:[1,0,0]
	v_cvt_scalef32_pk_f32_fp4 v[104:105], v89, 1.0 op_sel:[0,1,0]
	v_pk_fma_f32 v[102:103], v[92:93], v[102:103], v[106:107] op_sel_hi:[0,1,1]
	v_pk_fma_f32 v[104:105], v[92:93], v[104:105], v[108:109] op_sel_hi:[0,1,1]
	v_cvt_scalef32_pk_f32_fp4 v[88:89], v89, 1.0 op_sel:[1,1,0]
	v_pk_fma_f32 v[16:17], v[92:93], v[88:89], v[16:17] op_sel_hi:[0,1,1]
	s_waitcnt vmcnt(16)
	v_cvt_scalef32_pk_f32_fp4 v[92:93], v82, 1.0
	v_add_u32_e32 v89, 112, v255
	ds_bpermute_b32 v88, v89, v117
	s_waitcnt lgkmcnt(0)
	v_pk_fma_f32 v[216:217], v[92:93], v[88:89], v[18:19] op_sel_hi:[1,0,1]
	v_cvt_scalef32_pk_f32_fp4 v[18:19], v82, 1.0 op_sel:[1,0,0]
	v_pk_fma_f32 v[214:215], v[18:19], v[88:89], v[20:21] op_sel_hi:[1,0,1]
	v_cvt_scalef32_pk_f32_fp4 v[18:19], v82, 1.0 op_sel:[0,1,0]
	v_pk_fma_f32 v[212:213], v[18:19], v[88:89], v[22:23] op_sel_hi:[1,0,1]
	v_cvt_scalef32_pk_f32_fp4 v[18:19], v82, 1.0 op_sel:[1,1,0]
	v_pk_fma_f32 v[210:211], v[88:89], v[18:19], v[24:25] op_sel_hi:[0,1,1]
	v_cvt_scalef32_pk_f32_fp4 v[18:19], v83, 1.0
	v_pk_fma_f32 v[208:209], v[88:89], v[18:19], v[26:27] op_sel_hi:[0,1,1]
	v_cvt_scalef32_pk_f32_fp4 v[18:19], v83, 1.0 op_sel:[1,0,0]
	v_pk_fma_f32 v[206:207], v[88:89], v[18:19], v[28:29] op_sel_hi:[0,1,1]
	v_cvt_scalef32_pk_f32_fp4 v[18:19], v83, 1.0 op_sel:[0,1,0]
	v_pk_fma_f32 v[204:205], v[88:89], v[18:19], v[30:31] op_sel_hi:[0,1,1]
	v_cvt_scalef32_pk_f32_fp4 v[18:19], v83, 1.0 op_sel:[1,1,0]
	v_pk_fma_f32 v[202:203], v[88:89], v[18:19], v[86:87] op_sel_hi:[0,1,1]
	v_cvt_scalef32_pk_f32_fp4 v[18:19], v84, 1.0
	v_pk_fma_f32 v[200:201], v[88:89], v[18:19], v[90:91] op_sel_hi:[0,1,1]
	v_cvt_scalef32_pk_f32_fp4 v[18:19], v84, 1.0 op_sel:[1,0,0]
	v_pk_fma_f32 v[198:199], v[88:89], v[18:19], v[94:95] op_sel_hi:[0,1,1]
	v_cvt_scalef32_pk_f32_fp4 v[18:19], v84, 1.0 op_sel:[0,1,0]
	v_pk_fma_f32 v[196:197], v[88:89], v[18:19], v[96:97] op_sel_hi:[0,1,1]
	v_cvt_scalef32_pk_f32_fp4 v[18:19], v84, 1.0 op_sel:[1,1,0]
	v_pk_fma_f32 v[194:195], v[88:89], v[18:19], v[98:99] op_sel_hi:[0,1,1]
	v_cvt_scalef32_pk_f32_fp4 v[18:19], v85, 1.0
	v_pk_fma_f32 v[192:193], v[88:89], v[18:19], v[100:101] op_sel_hi:[0,1,1]
	v_cvt_scalef32_pk_f32_fp4 v[18:19], v85, 1.0 op_sel:[1,0,0]
	v_pk_fma_f32 v[190:191], v[88:89], v[18:19], v[102:103] op_sel_hi:[0,1,1]
	v_cvt_scalef32_pk_f32_fp4 v[18:19], v85, 1.0 op_sel:[0,1,0]
	v_pk_fma_f32 v[188:189], v[88:89], v[18:19], v[104:105] op_sel_hi:[0,1,1]
	v_cvt_scalef32_pk_f32_fp4 v[18:19], v85, 1.0 op_sel:[1,1,0]
	v_pk_fma_f32 v[176:177], v[88:89], v[18:19], v[16:17] op_sel_hi:[0,1,1]
	global_load_dwordx4 v[110:113], v0, s[52:53] offset:768
	global_load_dwordx4 v[106:109], v4, s[52:53] offset:768
	global_load_dwordx4 v[102:105], v2, s[52:53] offset:768
	global_load_dwordx4 v[98:101], v8, s[52:53] offset:768
	global_load_dwordx4 v[94:97], v6, s[52:53] offset:768
	global_load_dwordx4 v[90:93], v12, s[52:53] offset:768
	global_load_dwordx4 v[86:89], v10, s[52:53] offset:768
	global_load_dwordx4 v[82:85], v14, s[52:53] offset:768
	s_addk_i32 s24, 0x200
	s_cmpk_lg_i32 s24, 0xe00
	s_cbranch_scc0 .LBB0_334
.LBB0_330:
	s_waitcnt vmcnt(22)
	v_cvt_scalef32_pk32_f32_fp6 v[0:31], v[32:37], 1.0
	v_pk_fma_f32 v[0:1], v[0:1], v[152:153], 0 op_sel_hi:[1,1,0]
	v_pk_fma_f32 v[2:3], v[2:3], v[170:171], 0 op_sel_hi:[1,1,0]
	v_pk_fma_f32 v[0:1], v[4:5], v[148:149], v[0:1]
	v_pk_fma_f32 v[2:3], v[6:7], v[172:173], v[2:3]
	v_pk_fma_f32 v[0:1], v[8:9], v[144:145], v[0:1]
	v_pk_fma_f32 v[2:3], v[10:11], v[174:175], v[2:3]
	v_pk_fma_f32 v[0:1], v[12:13], v[140:141], v[0:1]
	v_pk_fma_f32 v[2:3], v[14:15], v[178:179], v[2:3]
	v_pk_fma_f32 v[0:1], v[16:17], v[168:169], v[0:1]
	v_pk_fma_f32 v[2:3], v[18:19], v[180:181], v[2:3]
	v_pk_fma_f32 v[0:1], v[20:21], v[164:165], v[0:1]
	v_pk_fma_f32 v[2:3], v[22:23], v[182:183], v[2:3]
	v_pk_fma_f32 v[0:1], v[24:25], v[160:161], v[0:1]
	v_pk_fma_f32 v[2:3], v[26:27], v[184:185], v[2:3]
	v_pk_fma_f32 v[0:1], v[28:29], v[156:157], v[0:1]
	v_pk_fma_f32 v[2:3], v[30:31], v[186:187], v[2:3]
	v_add_f32_e32 v4, v2, v3
	v_add_f32_e32 v5, v0, v1
	v_add_f32_e32 v117, v4, v5
	s_waitcnt vmcnt(20)
	v_cvt_scalef32_pk32_f32_fp6 v[0:31], v[38:43], 1.0
	v_pk_fma_f32 v[0:1], v[0:1], v[152:153], 0 op_sel_hi:[1,1,0]
	v_pk_fma_f32 v[2:3], v[2:3], v[170:171], 0 op_sel_hi:[1,1,0]
	v_pk_fma_f32 v[0:1], v[4:5], v[148:149], v[0:1]
	v_pk_fma_f32 v[2:3], v[6:7], v[172:173], v[2:3]
	v_pk_fma_f32 v[0:1], v[8:9], v[144:145], v[0:1]
	v_pk_fma_f32 v[2:3], v[10:11], v[174:175], v[2:3]
	v_pk_fma_f32 v[0:1], v[12:13], v[140:141], v[0:1]
	v_pk_fma_f32 v[2:3], v[14:15], v[178:179], v[2:3]
	v_pk_fma_f32 v[0:1], v[16:17], v[168:169], v[0:1]
	v_pk_fma_f32 v[2:3], v[18:19], v[180:181], v[2:3]
	v_pk_fma_f32 v[0:1], v[20:21], v[164:165], v[0:1]
	v_pk_fma_f32 v[2:3], v[22:23], v[182:183], v[2:3]
	v_pk_fma_f32 v[0:1], v[24:25], v[160:161], v[0:1]
	v_pk_fma_f32 v[2:3], v[26:27], v[184:185], v[2:3]
	v_pk_fma_f32 v[0:1], v[28:29], v[156:157], v[0:1]
	v_pk_fma_f32 v[2:3], v[30:31], v[186:187], v[2:3]
	v_add_f32_e32 v4, v2, v3
	v_add_f32_e32 v5, v0, v1
	v_add_f32_e32 v131, v4, v5
	s_waitcnt vmcnt(18)
	v_cvt_scalef32_pk32_f32_fp6 v[0:31], v[44:49], 1.0
	v_pk_fma_f32 v[0:1], v[0:1], v[152:153], 0 op_sel_hi:[1,1,0]
	v_pk_fma_f32 v[2:3], v[2:3], v[170:171], 0 op_sel_hi:[1,1,0]
	v_pk_fma_f32 v[0:1], v[4:5], v[148:149], v[0:1]
	v_pk_fma_f32 v[2:3], v[6:7], v[172:173], v[2:3]
	v_pk_fma_f32 v[0:1], v[8:9], v[144:145], v[0:1]
	v_pk_fma_f32 v[2:3], v[10:11], v[174:175], v[2:3]
	v_pk_fma_f32 v[0:1], v[12:13], v[140:141], v[0:1]
	v_pk_fma_f32 v[2:3], v[14:15], v[178:179], v[2:3]
	v_pk_fma_f32 v[0:1], v[16:17], v[168:169], v[0:1]
	v_pk_fma_f32 v[2:3], v[18:19], v[180:181], v[2:3]
	v_pk_fma_f32 v[0:1], v[20:21], v[164:165], v[0:1]
	v_pk_fma_f32 v[2:3], v[22:23], v[182:183], v[2:3]
	v_pk_fma_f32 v[0:1], v[24:25], v[160:161], v[0:1]
	v_pk_fma_f32 v[2:3], v[26:27], v[184:185], v[2:3]
	v_pk_fma_f32 v[0:1], v[28:29], v[156:157], v[0:1]
	v_pk_fma_f32 v[2:3], v[30:31], v[186:187], v[2:3]
	v_add_f32_e32 v4, v2, v3
	v_add_f32_e32 v5, v0, v1
	v_add_f32_e32 v133, v4, v5
	s_waitcnt vmcnt(16)
	v_cvt_scalef32_pk32_f32_fp6 v[0:31], v[50:55], 1.0
	v_pk_fma_f32 v[0:1], v[0:1], v[152:153], 0 op_sel_hi:[1,1,0]
	v_pk_fma_f32 v[2:3], v[2:3], v[170:171], 0 op_sel_hi:[1,1,0]
	v_pk_fma_f32 v[0:1], v[4:5], v[148:149], v[0:1]
	v_pk_fma_f32 v[2:3], v[6:7], v[172:173], v[2:3]
	v_pk_fma_f32 v[0:1], v[8:9], v[144:145], v[0:1]
	v_pk_fma_f32 v[2:3], v[10:11], v[174:175], v[2:3]
	v_pk_fma_f32 v[0:1], v[12:13], v[140:141], v[0:1]
	v_pk_fma_f32 v[2:3], v[14:15], v[178:179], v[2:3]
	v_pk_fma_f32 v[0:1], v[16:17], v[168:169], v[0:1]
	v_pk_fma_f32 v[2:3], v[18:19], v[180:181], v[2:3]
	v_pk_fma_f32 v[0:1], v[20:21], v[164:165], v[0:1]
	v_pk_fma_f32 v[2:3], v[22:23], v[182:183], v[2:3]
	v_pk_fma_f32 v[0:1], v[24:25], v[160:161], v[0:1]
	v_pk_fma_f32 v[2:3], v[26:27], v[184:185], v[2:3]
	v_pk_fma_f32 v[0:1], v[28:29], v[156:157], v[0:1]
	v_pk_fma_f32 v[2:3], v[30:31], v[186:187], v[2:3]
	v_add_f32_e32 v4, v2, v3
	v_add_f32_e32 v5, v0, v1
	v_add_f32_e32 v218, v4, v5
	s_waitcnt vmcnt(14)
	v_cvt_scalef32_pk32_f32_fp6 v[0:31], v[56:61], 1.0
	v_pk_fma_f32 v[0:1], v[0:1], v[152:153], 0 op_sel_hi:[1,1,0]
	v_pk_fma_f32 v[2:3], v[2:3], v[170:171], 0 op_sel_hi:[1,1,0]
	v_pk_fma_f32 v[0:1], v[4:5], v[148:149], v[0:1]
	v_pk_fma_f32 v[2:3], v[6:7], v[172:173], v[2:3]
	v_pk_fma_f32 v[0:1], v[8:9], v[144:145], v[0:1]
	v_pk_fma_f32 v[2:3], v[10:11], v[174:175], v[2:3]
	v_pk_fma_f32 v[0:1], v[12:13], v[140:141], v[0:1]
	v_pk_fma_f32 v[2:3], v[14:15], v[178:179], v[2:3]
	v_pk_fma_f32 v[0:1], v[16:17], v[168:169], v[0:1]
	v_pk_fma_f32 v[2:3], v[18:19], v[180:181], v[2:3]
	v_pk_fma_f32 v[0:1], v[20:21], v[164:165], v[0:1]
	v_pk_fma_f32 v[2:3], v[22:23], v[182:183], v[2:3]
	v_pk_fma_f32 v[0:1], v[24:25], v[160:161], v[0:1]
	v_pk_fma_f32 v[2:3], v[26:27], v[184:185], v[2:3]
	v_pk_fma_f32 v[0:1], v[28:29], v[156:157], v[0:1]
	v_pk_fma_f32 v[2:3], v[30:31], v[186:187], v[2:3]
	v_add_f32_e32 v4, v2, v3
	v_add_f32_e32 v5, v0, v1
	v_add_f32_e32 v219, v4, v5
	s_waitcnt vmcnt(12)
	v_cvt_scalef32_pk32_f32_fp6 v[0:31], v[62:67], 1.0
	v_pk_fma_f32 v[0:1], v[0:1], v[152:153], 0 op_sel_hi:[1,1,0]
	v_pk_fma_f32 v[2:3], v[2:3], v[170:171], 0 op_sel_hi:[1,1,0]
	v_pk_fma_f32 v[0:1], v[4:5], v[148:149], v[0:1]
	v_pk_fma_f32 v[2:3], v[6:7], v[172:173], v[2:3]
	v_pk_fma_f32 v[0:1], v[8:9], v[144:145], v[0:1]
	v_pk_fma_f32 v[2:3], v[10:11], v[174:175], v[2:3]
	v_pk_fma_f32 v[0:1], v[12:13], v[140:141], v[0:1]
	v_pk_fma_f32 v[2:3], v[14:15], v[178:179], v[2:3]
	v_pk_fma_f32 v[0:1], v[16:17], v[168:169], v[0:1]
	v_pk_fma_f32 v[2:3], v[18:19], v[180:181], v[2:3]
	v_pk_fma_f32 v[0:1], v[20:21], v[164:165], v[0:1]
	v_pk_fma_f32 v[2:3], v[22:23], v[182:183], v[2:3]
	v_pk_fma_f32 v[0:1], v[24:25], v[160:161], v[0:1]
	v_pk_fma_f32 v[2:3], v[26:27], v[184:185], v[2:3]
	v_pk_fma_f32 v[0:1], v[28:29], v[156:157], v[0:1]
	v_pk_fma_f32 v[2:3], v[30:31], v[186:187], v[2:3]
	v_add_f32_e32 v4, v2, v3
	v_add_f32_e32 v5, v0, v1
	v_add_f32_e32 v246, v4, v5
	s_waitcnt vmcnt(10)
	v_cvt_scalef32_pk32_f32_fp6 v[0:31], v[68:73], 1.0
	v_pk_fma_f32 v[0:1], v[0:1], v[152:153], 0 op_sel_hi:[1,1,0]
	v_pk_fma_f32 v[2:3], v[2:3], v[170:171], 0 op_sel_hi:[1,1,0]
	v_pk_fma_f32 v[0:1], v[4:5], v[148:149], v[0:1]
	v_pk_fma_f32 v[2:3], v[6:7], v[172:173], v[2:3]
	v_pk_fma_f32 v[0:1], v[8:9], v[144:145], v[0:1]
	v_pk_fma_f32 v[2:3], v[10:11], v[174:175], v[2:3]
	v_pk_fma_f32 v[0:1], v[12:13], v[140:141], v[0:1]
	v_pk_fma_f32 v[2:3], v[14:15], v[178:179], v[2:3]
	v_pk_fma_f32 v[0:1], v[16:17], v[168:169], v[0:1]
	v_pk_fma_f32 v[2:3], v[18:19], v[180:181], v[2:3]
	v_pk_fma_f32 v[0:1], v[20:21], v[164:165], v[0:1]
	v_pk_fma_f32 v[2:3], v[22:23], v[182:183], v[2:3]
	v_pk_fma_f32 v[0:1], v[24:25], v[160:161], v[0:1]
	v_pk_fma_f32 v[2:3], v[26:27], v[184:185], v[2:3]
	v_pk_fma_f32 v[0:1], v[28:29], v[156:157], v[0:1]
	v_pk_fma_f32 v[2:3], v[30:31], v[186:187], v[2:3]
	v_add_f32_e32 v4, v2, v3
	v_add_f32_e32 v5, v0, v1
	v_add_f32_e32 v247, v4, v5
	s_waitcnt vmcnt(8)
	v_cvt_scalef32_pk32_f32_fp6 v[0:31], v[74:79], 1.0
	v_pk_fma_f32 v[0:1], v[0:1], v[152:153], 0 op_sel_hi:[1,1,0]
	v_pk_fma_f32 v[2:3], v[2:3], v[170:171], 0 op_sel_hi:[1,1,0]
	v_pk_fma_f32 v[0:1], v[4:5], v[148:149], v[0:1]
	v_pk_fma_f32 v[2:3], v[6:7], v[172:173], v[2:3]
	v_pk_fma_f32 v[0:1], v[8:9], v[144:145], v[0:1]
	v_pk_fma_f32 v[2:3], v[10:11], v[174:175], v[2:3]
	v_pk_fma_f32 v[0:1], v[12:13], v[140:141], v[0:1]
	v_pk_fma_f32 v[2:3], v[14:15], v[178:179], v[2:3]
	v_pk_fma_f32 v[0:1], v[16:17], v[168:169], v[0:1]
	v_pk_fma_f32 v[2:3], v[18:19], v[180:181], v[2:3]
	v_pk_fma_f32 v[0:1], v[20:21], v[164:165], v[0:1]
	v_pk_fma_f32 v[2:3], v[22:23], v[182:183], v[2:3]
	v_pk_fma_f32 v[0:1], v[24:25], v[160:161], v[0:1]
	v_pk_fma_f32 v[2:3], v[26:27], v[184:185], v[2:3]
	v_pk_fma_f32 v[0:1], v[28:29], v[156:157], v[0:1]
	v_pk_fma_f32 v[2:3], v[30:31], v[186:187], v[2:3]
	v_add_f32_e32 v4, v2, v3
	v_add_f32_e32 v5, v0, v1
	v_add_f32_e32 v1, v4, v5
	v_add_u32_e32 v8, s24, v239
	ds_read_b32 v12, v8 offset:512
	s_waitcnt lgkmcnt(0)
	v_add_u32_e32 v13, 0, v255
	v_add_u32_e32 v15, 16, v255
	v_add_u32_e32 v18, 32, v255
	v_add_u32_e32 v19, 48, v255
	v_add_u32_e32 v20, 64, v255
	v_add_u32_e32 v21, 80, v255
	v_add_u32_e32 v26, 96, v255
	v_add_u32_e32 v27, 112, v255
	ds_bpermute_b32 v0, v13, v12
	ds_bpermute_b32 v2, v15, v12
	ds_bpermute_b32 v3, v18, v12
	ds_bpermute_b32 v6, v19, v12
	ds_bpermute_b32 v7, v20, v12
	ds_bpermute_b32 v10, v21, v12
	ds_bpermute_b32 v11, v26, v12
	ds_bpermute_b32 v14, v27, v12
	s_waitcnt lgkmcnt(7)
	v_mad_u32_u24 v22, v0, s28, v254
	global_load_dwordx2 v[36:37], v22, s[52:53] offset:16
	global_load_dwordx4 v[32:35], v22, s[52:53]
	s_waitcnt lgkmcnt(6)
	v_mad_u32_u24 v24, v2, s28, v254
	global_load_dwordx2 v[42:43], v24, s[52:53] offset:16
	global_load_dwordx4 v[38:41], v24, s[52:53]
	s_waitcnt lgkmcnt(5)
	v_mad_u32_u24 v22, v3, s28, v254
	global_load_dwordx2 v[48:49], v22, s[52:53] offset:16
	global_load_dwordx4 v[44:47], v22, s[52:53]
	s_waitcnt lgkmcnt(4)
	v_mad_u32_u24 v24, v6, s28, v254
	global_load_dwordx2 v[54:55], v24, s[52:53] offset:16
	global_load_dwordx4 v[50:53], v24, s[52:53]
	s_waitcnt lgkmcnt(3)
	v_mad_u32_u24 v22, v7, s28, v254
	global_load_dwordx2 v[60:61], v22, s[52:53] offset:16
	global_load_dwordx4 v[56:59], v22, s[52:53]
	s_waitcnt lgkmcnt(2)
	v_mad_u32_u24 v24, v10, s28, v254
	global_load_dwordx2 v[66:67], v24, s[52:53] offset:16
	global_load_dwordx4 v[62:65], v24, s[52:53]
	s_waitcnt lgkmcnt(1)
	v_mad_u32_u24 v22, v11, s28, v254
	global_load_dwordx2 v[72:73], v22, s[52:53] offset:16
	global_load_dwordx4 v[68:71], v22, s[52:53]
	s_waitcnt lgkmcnt(0)
	v_mad_u32_u24 v24, v14, s28, v254
	global_load_dwordx2 v[78:79], v24, s[52:53] offset:16
	global_load_dwordx4 v[74:77], v24, s[52:53]
	ds_read_b64 v[16:17], v8
	v_cndmask_b32_e64 v4, v117, v219, s[14:15]
	ds_bpermute_b32 v4, v242, v4
	v_cndmask_b32_e64 v5, v219, v117, s[14:15]
	v_cndmask_b32_e64 v8, v131, v246, s[14:15]
	ds_bpermute_b32 v8, v242, v8
	v_cndmask_b32_e64 v12, v218, v1, s[14:15]
	s_waitcnt lgkmcnt(1)
	v_add_f32_e32 v4, v5, v4
	v_cndmask_b32_e64 v5, v133, v247, s[14:15]
	ds_bpermute_b32 v5, v242, v5
	ds_bpermute_b32 v12, v242, v12
	v_cndmask_b32_e64 v9, v246, v131, s[14:15]
	s_waitcnt lgkmcnt(2)
	v_add_f32_e32 v8, v9, v8
	v_cndmask_b32_e64 v9, v247, v133, s[14:15]
	v_cndmask_b32_e64 v1, v1, v218, s[14:15]
	s_waitcnt lgkmcnt(1)
	v_add_f32_e32 v5, v9, v5
	s_waitcnt lgkmcnt(0)
	v_add_f32_e32 v1, v1, v12
	v_cndmask_b32_e64 v9, v4, v5, s[16:17]
	v_cndmask_b32_e64 v12, v8, v1, s[16:17]
	ds_bpermute_b32 v9, v241, v9
	ds_bpermute_b32 v12, v241, v12
	v_cndmask_b32_e64 v4, v5, v4, s[16:17]
	v_cndmask_b32_e64 v1, v1, v8, s[16:17]
	s_waitcnt lgkmcnt(1)
	v_add_f32_e32 v4, v4, v9
	s_waitcnt lgkmcnt(0)
	v_add_f32_e32 v1, v1, v12
	v_cndmask_b32_e64 v5, v4, v1, s[18:19]
	ds_bpermute_b32 v5, v240, v5
	v_cndmask_b32_e64 v1, v1, v4, s[18:19]
	s_waitcnt lgkmcnt(0)
	v_add_f32_e32 v1, v1, v5
	ds_bpermute_b32 v4, v244, v1
	s_waitcnt lgkmcnt(0)
	v_add_f32_e32 v1, v1, v4
	ds_bpermute_b32 v4, v245, v1
	s_waitcnt lgkmcnt(0)
	v_add_f32_e32 v1, v1, v4
	v_mul_f32_e32 v18, 0x3caaaaab, v1
	v_mul_f32_e32 v16, 0x3f3504f3, v18
	v_cmp_nlt_f32_e64 s[2:3], |v16|, 1.0
	s_and_saveexec_b64 s[26:27], s[2:3]
	s_xor_b64 s[2:3], exec, s[26:27]
	s_cbranch_execz .LBB0_332
	s_mov_b32 s25, 0x378e98ab
	v_fma_f32 v1, |v16|, s25, v233
	s_mov_b32 s25, 0x3b7cd369
	v_fma_f32 v1, |v16|, v1, s25
	s_mov_b32 s25, 0xbcc618b2
	v_fma_f32 v1, |v16|, v1, s25
	s_mov_b32 s25, 0x3dda74e4
	v_fma_f32 v1, |v16|, v1, s25
	s_mov_b32 s25, 0x3f228afd
	v_fma_f32 v1, |v16|, v1, s25
	s_mov_b32 s25, 0x3e03c728
	v_fma_f32 v1, |v16|, v1, s25
	v_fma_f32 v1, |v16|, v1, |v16|
	v_mul_f32_e32 v4, 0xbfb8aa3b, v1
	s_mov_b32 s25, 0xbfb8aa3b
	v_fma_f32 v5, v1, s25, -v4
	v_rndne_f32_e32 v8, v4
	v_fmac_f32_e32 v5, 0xb2a5705f, v1
	v_sub_f32_e32 v4, v4, v8
	v_add_f32_e32 v4, v4, v5
	v_cvt_i32_f32_e32 v5, v8
	v_exp_f32_e32 v4, v4
	s_mov_b32 s25, 0x42ce8ed0
	v_cmp_nlt_f32_e32 vcc, s25, v1
	s_mov_b32 s25, 0xc2b17218
	v_ldexp_f32 v4, v4, v5
	v_cndmask_b32_e32 v4, 0, v4, vcc
	v_cmp_ngt_f32_e32 vcc, s25, v1
	s_nop 1
	v_cndmask_b32_e32 v1, v234, v4, vcc
	v_sub_f32_e32 v19, 1.0, v1
